# byte-phase pin (guide 9.3): s_nop pads so the four rolled K-loop heads sit at the baseline's byte offsets mod 64; rest as v166
# speedup vs baseline: 1.0052x; 1.0009x over previous
;     __device__ __forceinline__ bool next(int i, Unit& u) const { if (i != 0) return false; return base.next(which, u); }
;     __device__ __forceinline__ bool next(int i, Unit& u) const { if (i >= nrd) return false; u.pm = (rd0 + i) * 16 + 4 * xl + (j >> 3); u.pn = j & 7; return true; }
; template <class Epi, class Sched, bool ALIGN_EPI = false, bool SP2 = false>
; __device__ __forceinline__ void gemm_phase(PG8_LAS unsigned char* lds, const Gemm g, const Sched& S, const Epi& E, const int wave_id) {
;     ...
;     Unit cur, nxt; int ui = 0;
;     if (!S.next(0, cur)) return;
;     f32x4 acc[2][2][4][2];
; #pragma unroll
;     for (int a = 0; a < 2; ++a)
; #pragma unroll
;         for (int b = 0; b < 2; ++b)
; #pragma unroll
;             for (int m = 0; m < 4; ++m)
; #pragma unroll
;                 for (int n = 0; n < 2; ++n) acc[a][b][m][n] = (f32x4){0.f, 0.f, 0.f, 0.f};
;     bf16x8 At[4][2], B0[2][2], B1[2][2];
;     const char* cA = (const char*)g.A + (size_t)cur.pm * tstep; const char* cB = (const char*)g.Bt + (size_t)cur.pn * tstep;
;     ...
; #pragma unroll
;         for (int a = 0; a < 2; ++a)
; #pragma unroll
;             for (int b = 0; b < 2; ++b)
; #pragma unroll
;                 for (int m = 0; m < 4; ++m)
; #pragma unroll
;                     for (int n = 0; n < 2; ++n) acc[a][b][m][n] = (f32x4){0.f, 0.f, 0.f, 0.f};
;         cur = nxt; cA = nA; cB = nB; ++ui;
.LBB0_171:
	s_ashr_i32 s37, s36, 31
	s_lshl_b64 s[42:43], s[36:37], 20
	s_add_u32 s42, s10, s42
	s_addc_u32 s43, s11, s43
	s_and_b64 s[44:45], s[0:1], exec
	s_cselect_b32 s5, s43, s47
	s_cselect_b32 s7, s42, s46
	s_ashr_i32 s41, s40, 31
	s_lshl_b64 s[44:45], s[40:41], 20
	s_add_u32 s44, s62, s44
	s_addc_u32 s45, s63, s45
	s_and_b64 s[50:51], s[0:1], exec
	s_cselect_b32 s37, s45, s49
	s_cselect_b32 s41, s44, s48
	s_add_u32 s46, s46, 0x80080
	s_addc_u32 s47, s47, 0
	s_add_u32 s67, s48, 0x100
	v_mov_b32_e32 v0, 0
	s_addc_u32 s78, s49, 0
	s_mov_b32 s79, -2
	v_mov_b32_e32 v1, v0
	v_mov_b32_e32 v2, v0
	v_mov_b32_e32 v3, v0
	v_mov_b32_e32 v4, v0
	v_mov_b32_e32 v5, v0
	v_mov_b32_e32 v6, v0
	v_mov_b32_e32 v7, v0
	v_mov_b32_e32 v16, v0
	v_mov_b32_e32 v17, v0
	v_mov_b32_e32 v18, v0
	v_mov_b32_e32 v19, v0
	v_mov_b32_e32 v20, v0
	v_mov_b32_e32 v21, v0
	v_mov_b32_e32 v22, v0
	v_mov_b32_e32 v23, v0
	v_mov_b32_e32 v32, v0
	v_mov_b32_e32 v33, v0
	v_mov_b32_e32 v34, v0
	v_mov_b32_e32 v35, v0
	v_mov_b32_e32 v36, v0
	v_mov_b32_e32 v37, v0
	v_mov_b32_e32 v38, v0
	v_mov_b32_e32 v39, v0
	v_mov_b32_e32 v48, v0
	v_mov_b32_e32 v49, v0
	v_mov_b32_e32 v50, v0
	v_mov_b32_e32 v51, v0
	v_mov_b32_e32 v52, v0
	v_mov_b32_e32 v53, v0
	v_mov_b32_e32 v54, v0
	v_mov_b32_e32 v55, v0
	v_mov_b32_e32 v8, v0
	v_mov_b32_e32 v9, v0
	v_mov_b32_e32 v10, v0
	v_mov_b32_e32 v11, v0
	v_mov_b32_e32 v12, v0
	v_mov_b32_e32 v13, v0
	v_mov_b32_e32 v14, v0
	v_mov_b32_e32 v15, v0
	v_mov_b32_e32 v24, v0
	v_mov_b32_e32 v25, v0
	v_mov_b32_e32 v26, v0
	v_mov_b32_e32 v27, v0
	v_mov_b32_e32 v28, v0
	v_mov_b32_e32 v29, v0
	v_mov_b32_e32 v30, v0
	v_mov_b32_e32 v31, v0
	v_mov_b32_e32 v40, v0
	v_mov_b32_e32 v41, v0
	v_mov_b32_e32 v42, v0
	v_mov_b32_e32 v43, v0
	v_mov_b32_e32 v44, v0
	v_mov_b32_e32 v45, v0
	v_mov_b32_e32 v46, v0
	v_mov_b32_e32 v47, v0
	v_mov_b32_e32 v56, v0
	v_mov_b32_e32 v57, v0
	v_mov_b32_e32 v58, v0
	v_mov_b32_e32 v59, v0
	v_mov_b32_e32 v60, v0
	v_mov_b32_e32 v61, v0
	v_mov_b32_e32 v62, v0
	v_mov_b32_e32 v63, v0
	v_mov_b32_e32 v64, v0
	v_mov_b32_e32 v65, v0
	v_mov_b32_e32 v66, v0
	v_mov_b32_e32 v67, v0
	v_mov_b32_e32 v68, v0
	v_mov_b32_e32 v69, v0
	v_mov_b32_e32 v70, v0
	v_mov_b32_e32 v71, v0
	v_mov_b32_e32 v80, v0
	v_mov_b32_e32 v81, v0
	v_mov_b32_e32 v82, v0
	v_mov_b32_e32 v83, v0
	v_mov_b32_e32 v84, v0
	v_mov_b32_e32 v85, v0
	v_mov_b32_e32 v86, v0
	v_mov_b32_e32 v87, v0
	v_mov_b32_e32 v96, v0
	v_mov_b32_e32 v97, v0
	v_mov_b32_e32 v98, v0
	v_mov_b32_e32 v99, v0
	v_mov_b32_e32 v100, v0
	v_mov_b32_e32 v101, v0
	v_mov_b32_e32 v102, v0
	v_mov_b32_e32 v103, v0
	v_mov_b32_e32 v112, v0
	v_mov_b32_e32 v113, v0
	v_mov_b32_e32 v114, v0
	v_mov_b32_e32 v115, v0
	v_mov_b32_e32 v116, v0
	v_mov_b32_e32 v117, v0
	v_mov_b32_e32 v118, v0
	v_mov_b32_e32 v119, v0
	v_mov_b32_e32 v72, v0
	v_mov_b32_e32 v73, v0
	v_mov_b32_e32 v74, v0
	v_mov_b32_e32 v75, v0
	v_mov_b32_e32 v76, v0
	v_mov_b32_e32 v77, v0
	v_mov_b32_e32 v78, v0
	v_mov_b32_e32 v79, v0
	v_mov_b32_e32 v88, v0
	v_mov_b32_e32 v89, v0
	v_mov_b32_e32 v90, v0
	v_mov_b32_e32 v91, v0
	v_mov_b32_e32 v92, v0
	v_mov_b32_e32 v93, v0
	v_mov_b32_e32 v94, v0
	v_mov_b32_e32 v95, v0
	v_mov_b32_e32 v104, v0
	v_mov_b32_e32 v105, v0
	v_mov_b32_e32 v106, v0
	v_mov_b32_e32 v107, v0
	v_mov_b32_e32 v108, v0
	v_mov_b32_e32 v109, v0
	v_mov_b32_e32 v110, v0
	v_mov_b32_e32 v111, v0
	v_mov_b32_e32 v120, v0
	v_mov_b32_e32 v121, v0
	v_mov_b32_e32 v122, v0
	v_mov_b32_e32 v123, v0
	v_mov_b32_e32 v124, v0
	v_mov_b32_e32 v125, v0
	v_mov_b32_e32 v126, v0
	v_mov_b32_e32 v127, v0
	s_nop 0
	s_nop 0
	s_nop 0
	s_nop 0
	s_nop 0
	s_nop 0
	s_nop 0
	s_nop 0
	s_nop 0
	s_nop 0

; template <class Epi, class Sched, bool ALIGN_EPI = false, bool SP2 = false>
; __device__ __forceinline__ void gemm_phase(PG8_LAS unsigned char* lds, const Gemm g, const Sched& S, const Epi& E, const int wave_id) {
;     ...
; #pragma unroll
;         for (int a = 0; a < 2; ++a)
; #pragma unroll
;             for (int b = 0; b < 2; ++b)
; #pragma unroll
;                 for (int m = 0; m < 4; ++m)
; #pragma unroll
;                     for (int n = 0; n < 2; ++n) acc[a][b][m][n] = (f32x4){0.f, 0.f, 0.f, 0.f};
;         cur = nxt; cA = nA; cB = nB; ++ui;
.LBB0_449:
	s_mov_b32 s24, s42
	s_mov_b32 s0, s42
	s_add_i32 s42, s1, s12
	s_mov_b64 s[22:23], s[14:15]
	s_and_b64 s[14:15], s[20:21], exec
	s_cselect_b32 s14, s42, s24
	s_ashr_i32 s15, s14, 31
	s_lshl_b64 s[14:15], s[14:15], 19
	s_add_u32 s14, s38, s14
	s_addc_u32 s15, s39, s15
	s_and_b64 s[24:25], s[20:21], exec
	v_mov_b32_e32 v0, 0
	s_cselect_b32 s1, s15, s23
	s_cselect_b32 s43, s14, s22
	v_lshl_add_u64 v[112:113], s[22:23], 0, v[172:173]
	v_lshl_add_u64 v[114:115], s[22:23], 0, v[174:175]
	s_mov_b32 s44, -2
	s_mov_b64 s[24:25], 0
	v_mov_b32_e32 v1, v0
	v_mov_b32_e32 v2, v0
	v_mov_b32_e32 v3, v0
	v_mov_b32_e32 v8, v0
	v_mov_b32_e32 v9, v0
	v_mov_b32_e32 v10, v0
	v_mov_b32_e32 v11, v0
	v_mov_b32_e32 v16, v0
	v_mov_b32_e32 v17, v0
	v_mov_b32_e32 v18, v0
	v_mov_b32_e32 v19, v0
	v_mov_b32_e32 v24, v0
	v_mov_b32_e32 v25, v0
	v_mov_b32_e32 v26, v0
	v_mov_b32_e32 v27, v0
	v_mov_b32_e32 v32, v0
	v_mov_b32_e32 v33, v0
	v_mov_b32_e32 v34, v0
	v_mov_b32_e32 v35, v0
	v_mov_b32_e32 v40, v0
	v_mov_b32_e32 v41, v0
	v_mov_b32_e32 v42, v0
	v_mov_b32_e32 v43, v0
	v_mov_b32_e32 v48, v0
	v_mov_b32_e32 v49, v0
	v_mov_b32_e32 v50, v0
	v_mov_b32_e32 v51, v0
	v_mov_b32_e32 v56, v0
	v_mov_b32_e32 v57, v0
	v_mov_b32_e32 v58, v0
	v_mov_b32_e32 v59, v0
	v_mov_b32_e32 v4, v0
	v_mov_b32_e32 v5, v0
	v_mov_b32_e32 v6, v0
	v_mov_b32_e32 v7, v0
	v_mov_b32_e32 v12, v0
	v_mov_b32_e32 v13, v0
	v_mov_b32_e32 v14, v0
	v_mov_b32_e32 v15, v0
	v_mov_b32_e32 v20, v0
	v_mov_b32_e32 v21, v0
	v_mov_b32_e32 v22, v0
	v_mov_b32_e32 v23, v0
	v_mov_b32_e32 v28, v0
	v_mov_b32_e32 v29, v0
	v_mov_b32_e32 v30, v0
	v_mov_b32_e32 v31, v0
	v_mov_b32_e32 v36, v0
	v_mov_b32_e32 v37, v0
	v_mov_b32_e32 v38, v0
	v_mov_b32_e32 v39, v0
	v_mov_b32_e32 v44, v0
	v_mov_b32_e32 v45, v0
	v_mov_b32_e32 v46, v0
	v_mov_b32_e32 v47, v0
	v_mov_b32_e32 v52, v0
	v_mov_b32_e32 v53, v0
	v_mov_b32_e32 v54, v0
	v_mov_b32_e32 v55, v0
	v_mov_b32_e32 v60, v0
	v_mov_b32_e32 v61, v0
	v_mov_b32_e32 v62, v0
	v_mov_b32_e32 v63, v0
	v_mov_b32_e32 v64, v0
	v_mov_b32_e32 v65, v0
	v_mov_b32_e32 v66, v0
	v_mov_b32_e32 v67, v0
	v_mov_b32_e32 v72, v0
	v_mov_b32_e32 v73, v0
	v_mov_b32_e32 v74, v0
	v_mov_b32_e32 v75, v0
	v_mov_b32_e32 v80, v0
	v_mov_b32_e32 v81, v0
	v_mov_b32_e32 v82, v0
	v_mov_b32_e32 v83, v0
	v_mov_b32_e32 v88, v0
	v_mov_b32_e32 v89, v0
	v_mov_b32_e32 v90, v0
	v_mov_b32_e32 v91, v0
	v_mov_b32_e32 v96, v0
	v_mov_b32_e32 v97, v0
	v_mov_b32_e32 v98, v0
	v_mov_b32_e32 v99, v0
	v_mov_b32_e32 v104, v0
	v_mov_b32_e32 v105, v0
	v_mov_b32_e32 v106, v0
	v_mov_b32_e32 v107, v0
	v_mov_b32_e32 v116, v0
	v_mov_b32_e32 v117, v0
	v_mov_b32_e32 v118, v0
	v_mov_b32_e32 v119, v0
	v_mov_b32_e32 v124, v0
	v_mov_b32_e32 v125, v0
	v_mov_b32_e32 v126, v0
	v_mov_b32_e32 v127, v0
	v_mov_b32_e32 v68, v0
	v_mov_b32_e32 v69, v0
	v_mov_b32_e32 v70, v0
	v_mov_b32_e32 v71, v0
	v_mov_b32_e32 v76, v0
	v_mov_b32_e32 v77, v0
	v_mov_b32_e32 v78, v0
	v_mov_b32_e32 v79, v0
	v_mov_b32_e32 v84, v0
	v_mov_b32_e32 v85, v0
	v_mov_b32_e32 v86, v0
	v_mov_b32_e32 v87, v0
	v_mov_b32_e32 v92, v0
	v_mov_b32_e32 v93, v0
	v_mov_b32_e32 v94, v0
	v_mov_b32_e32 v95, v0
	v_mov_b32_e32 v100, v0
	v_mov_b32_e32 v101, v0
	v_mov_b32_e32 v102, v0
	v_mov_b32_e32 v103, v0
	v_mov_b32_e32 v108, v0
	v_mov_b32_e32 v109, v0
	v_mov_b32_e32 v110, v0
	v_mov_b32_e32 v111, v0
	v_mov_b32_e32 v120, v0
	v_mov_b32_e32 v121, v0
	v_mov_b32_e32 v122, v0
	v_mov_b32_e32 v123, v0
	v_mov_b32_e32 v128, v0
	v_mov_b32_e32 v129, v0
	v_mov_b32_e32 v130, v0
	v_mov_b32_e32 v131, v0
	s_nop 0
	s_nop 0
	s_nop 0
	s_nop 0
	s_nop 0
	s_nop 0
	s_nop 0
	s_nop 0
	s_nop 0

;     __device__ __forceinline__ bool next(int i, Unit& u) const { if (i != 0) return false; return base.next(which, u); }
;     __device__ __forceinline__ bool next(int i, Unit& u) const { if (i >= nrd) return false; u.pm = (rd0 + i) * 16 + 4 * xl + (j >> 3); u.pn = j & 7; return true; }
; template <class Epi, class Sched, bool ALIGN_EPI = false, bool SP2 = false>
; __device__ __forceinline__ void gemm_phase(PG8_LAS unsigned char* lds, const Gemm g, const Sched& S, const Epi& E, const int wave_id) {
;     ...
;         const bool has_next = S.next(ui + 1, nxt);
;         const char* nA = has_next ? (const char*)g.A + (size_t)nxt.pm * tstep : cA; const char* nB = has_next ? (const char*)g.Bt + (size_t)nxt.pn * tstep : cB;
;     ...
; #pragma unroll
;         for (int a = 0; a < 2; ++a)
; #pragma unroll
;             for (int b = 0; b < 2; ++b)
; #pragma unroll
;                 for (int m = 0; m < 4; ++m)
; #pragma unroll
;                     for (int n = 0; n < 2; ++n) acc[a][b][m][n] = (f32x4){0.f, 0.f, 0.f, 0.f};
;         cur = nxt; cA = nA; cB = nB; ++ui;
.LBB0_521:
	s_mov_b32 s49, s0
	s_mov_b32 s1, s0
	s_add_i32 s0, s48, s12
	s_mov_b64 s[46:47], s[40:41]
	s_and_b64 s[40:41], s[10:11], exec
	s_cselect_b32 s40, s0, s49
	s_ashr_i32 s41, s40, 31
	s_lshl_b64 s[40:41], s[40:41], 20
	s_add_u32 s40, s6, s40
	s_addc_u32 s41, s7, s41
	s_and_b64 s[48:49], s[10:11], exec
	s_cselect_b32 vcc_lo, s41, s47
	s_cselect_b32 vcc_hi, s40, s46
	v_lshl_add_u64 v[128:129], s[46:47], 0, v[182:183]
	v_lshl_add_u64 v[130:131], s[46:47], 0, v[184:185]
	s_mov_b32 s58, -2
	s_mov_b64 s[48:49], 0
	v_mov_b32_e32 v0, 0
	v_mov_b32_e32 v1, v177
	v_mov_b32_e32 v2, v177
	v_mov_b32_e32 v3, v177
	v_mov_b32_e32 v4, 0
	v_mov_b32_e32 v5, v177
	v_mov_b32_e32 v6, v177
	v_mov_b32_e32 v7, v177
	v_mov_b32_e32 v16, 0
	v_mov_b32_e32 v17, v177
	v_mov_b32_e32 v18, v177
	v_mov_b32_e32 v19, v177
	v_mov_b32_e32 v20, 0
	v_mov_b32_e32 v21, v177
	v_mov_b32_e32 v22, v177
	v_mov_b32_e32 v23, v177
	v_mov_b32_e32 v32, 0
	v_mov_b32_e32 v33, v177
	v_mov_b32_e32 v34, v177
	v_mov_b32_e32 v35, v177
	v_mov_b32_e32 v36, 0
	v_mov_b32_e32 v37, v177
	v_mov_b32_e32 v38, v177
	v_mov_b32_e32 v39, v177
	v_mov_b32_e32 v48, 0
	v_mov_b32_e32 v49, v177
	v_mov_b32_e32 v50, v177
	v_mov_b32_e32 v51, v177
	v_mov_b32_e32 v52, 0
	v_mov_b32_e32 v53, v177
	v_mov_b32_e32 v54, v177
	v_mov_b32_e32 v55, v177
	v_mov_b32_e32 v8, 0
	v_mov_b32_e32 v9, v177
	v_mov_b32_e32 v10, v177
	v_mov_b32_e32 v11, v177
	v_mov_b32_e32 v12, 0
	v_mov_b32_e32 v13, v177
	v_mov_b32_e32 v14, v177
	v_mov_b32_e32 v15, v177
	v_mov_b32_e32 v24, 0
	v_mov_b32_e32 v25, v177
	v_mov_b32_e32 v26, v177
	v_mov_b32_e32 v27, v177
	v_mov_b32_e32 v28, 0
	v_mov_b32_e32 v29, v177
	v_mov_b32_e32 v30, v177
	v_mov_b32_e32 v31, v177
	v_mov_b32_e32 v40, 0
	v_mov_b32_e32 v41, v177
	v_mov_b32_e32 v42, v177
	v_mov_b32_e32 v43, v177
	v_mov_b32_e32 v44, 0
	v_mov_b32_e32 v45, v177
	v_mov_b32_e32 v46, v177
	v_mov_b32_e32 v47, v177
	v_mov_b32_e32 v56, 0
	v_mov_b32_e32 v57, v177
	v_mov_b32_e32 v58, v177
	v_mov_b32_e32 v59, v177
	v_mov_b32_e32 v60, 0
	v_mov_b32_e32 v61, v177
	v_mov_b32_e32 v62, v177
	v_mov_b32_e32 v63, v177
	v_mov_b32_e32 v64, 0
	v_mov_b32_e32 v65, v177
	v_mov_b32_e32 v66, v177
	v_mov_b32_e32 v67, v177
	v_mov_b32_e32 v68, 0
	v_mov_b32_e32 v69, v177
	v_mov_b32_e32 v70, v177
	v_mov_b32_e32 v71, v177
	v_mov_b32_e32 v80, 0
	v_mov_b32_e32 v81, v177
	v_mov_b32_e32 v82, v177
	v_mov_b32_e32 v83, v177
	v_mov_b32_e32 v84, 0
	v_mov_b32_e32 v85, v177
	v_mov_b32_e32 v86, v177
	v_mov_b32_e32 v87, v177
	v_mov_b32_e32 v96, 0
	v_mov_b32_e32 v97, v177
	v_mov_b32_e32 v98, v177
	v_mov_b32_e32 v99, v177
	v_mov_b32_e32 v100, 0
	v_mov_b32_e32 v101, v177
	v_mov_b32_e32 v102, v177
	v_mov_b32_e32 v103, v177
	v_mov_b32_e32 v112, 0
	v_mov_b32_e32 v113, v177
	v_mov_b32_e32 v114, v177
	v_mov_b32_e32 v115, v177
	v_mov_b32_e32 v116, 0
	v_mov_b32_e32 v117, v177
	v_mov_b32_e32 v118, v177
	v_mov_b32_e32 v119, v177
	v_mov_b32_e32 v72, 0
	v_mov_b32_e32 v73, v177
	v_mov_b32_e32 v74, v177
	v_mov_b32_e32 v75, v177
	v_mov_b32_e32 v76, 0
	v_mov_b32_e32 v77, v177
	v_mov_b32_e32 v78, v177
	v_mov_b32_e32 v79, v177
	v_mov_b32_e32 v88, 0
	v_mov_b32_e32 v89, v177
	v_mov_b32_e32 v90, v177
	v_mov_b32_e32 v91, v177
	v_mov_b32_e32 v92, 0
	v_mov_b32_e32 v93, v177
	v_mov_b32_e32 v94, v177
	v_mov_b32_e32 v95, v177
	v_mov_b32_e32 v104, 0
	v_mov_b32_e32 v105, v177
	v_mov_b32_e32 v106, v177
	v_mov_b32_e32 v107, v177
	v_mov_b32_e32 v108, 0
	v_mov_b32_e32 v109, v177
	v_mov_b32_e32 v110, v177
	v_mov_b32_e32 v111, v177
	v_mov_b32_e32 v120, 0
	v_mov_b32_e32 v121, v177
	v_mov_b32_e32 v122, v177
	v_mov_b32_e32 v123, v177
	v_mov_b32_e32 v124, 0
	v_mov_b32_e32 v125, v177
	v_mov_b32_e32 v126, v177
	v_mov_b32_e32 v127, v177
	s_nop 0
	s_nop 0
	s_nop 0
	s_nop 0
